# rows-phase rope xor16 via permlane16 swap+select; barrier members poll the global generation word directly
# speedup vs baseline: 1.0266x; 1.0010x over previous
.LBB0_279:
	s_or_b64 exec, exec, s[8:9]
	v_cvt_f32_u32_e32 v5, v3
	s_waitcnt vmcnt(0)
	v_readfirstlane_b32 s2, v4
	v_sub_u32_e32 v4, 0, v3
	v_rcp_iflag_f32_e32 v5, v5
	v_add_u32_e32 v6, s2, v2
	v_mul_f32_e32 v5, 0x4f7ffffe, v5
	v_cvt_u32_f32_e32 v5, v5
	v_mul_lo_u32 v2, v4, v5
	v_mul_hi_u32 v2, v5, v2
	v_add_u32_e32 v2, v5, v2
	v_mul_hi_u32 v2, v6, v2
	v_mul_lo_u32 v4, v2, v3
	v_sub_u32_e32 v4, v6, v4
	v_add_u32_e32 v5, 1, v2
	v_cmp_ge_u32_e32 vcc, v4, v3
	s_nop 1
	v_cndmask_b32_e32 v2, v2, v5, vcc
	v_sub_u32_e32 v5, v4, v3
	v_cndmask_b32_e32 v4, v4, v5, vcc
	v_add_u32_e32 v5, 1, v2
	v_cmp_ge_u32_e32 vcc, v4, v3
	v_add_u32_e32 v4, 1, v6
	s_nop 0
	v_cndmask_b32_e32 v2, v2, v5, vcc
	v_mul_lo_u32 v5, v3, v2
	v_add_u32_e32 v3, v5, v3
	v_cmp_ne_u32_e32 vcc, v4, v3
	s_and_saveexec_b64 s[6:7], vcc
	s_xor_b64 s[6:7], exec, s[6:7]
	s_cbranch_execz .LBB0_293
	s_waitcnt lgkmcnt(0)
	v_mov_b32_e32 v1, 0x7500
	global_load_dword v1, v1, s[86:87] sc1
	s_add_u32 s12, s86, 0x7500
	s_addc_u32 s13, s87, 0
	s_waitcnt vmcnt(0)
	v_cmp_eq_u32_e32 vcc, v1, v2
	s_and_saveexec_b64 s[8:9], vcc
	s_cbranch_execz .LBB0_292
	s_add_u32 s10, s86, 0x4200
	s_addc_u32 s11, s87, 0
	s_mov_b32 s2, 1
	s_mov_b64 s[16:17], 0
	v_mov_b32_e32 v1, 0
	s_branch .LBB0_283

.LBB0_373:
	s_or_b64 exec, exec, s[36:37]
	v_cvt_f32_u32_e32 v6, v4
	s_waitcnt vmcnt(0)
	v_readfirstlane_b32 s2, v5
	v_sub_u32_e32 v5, 0, v4
	v_rcp_iflag_f32_e32 v6, v6
	v_add_u32_e32 v7, s2, v3
	v_mul_f32_e32 v6, 0x4f7ffffe, v6
	v_cvt_u32_f32_e32 v6, v6
	v_mul_lo_u32 v3, v5, v6
	v_mul_hi_u32 v3, v6, v3
	v_add_u32_e32 v3, v6, v3
	v_mul_hi_u32 v3, v7, v3
	v_mul_lo_u32 v5, v3, v4
	v_sub_u32_e32 v5, v7, v5
	v_add_u32_e32 v6, 1, v3
	v_cmp_ge_u32_e32 vcc, v5, v4
	s_nop 1
	v_cndmask_b32_e32 v3, v3, v6, vcc
	v_sub_u32_e32 v6, v5, v4
	v_cndmask_b32_e32 v5, v5, v6, vcc
	v_add_u32_e32 v6, 1, v3
	v_cmp_ge_u32_e32 vcc, v5, v4
	v_add_u32_e32 v5, 1, v7
	s_nop 0
	v_cndmask_b32_e32 v3, v3, v6, vcc
	v_mul_lo_u32 v6, v4, v3
	v_add_u32_e32 v4, v6, v4
	v_cmp_ne_u32_e32 vcc, v5, v4
	s_and_saveexec_b64 s[8:9], vcc
	s_xor_b64 s[36:37], exec, s[8:9]
	s_cbranch_execz .LBB0_387
	v_readlane_b32 s8, v251, 30
	v_readlane_b32 s9, v251, 31
	s_waitcnt lgkmcnt(0)
	s_nop 3
	global_load_dword v2, v99, s[8:9] sc1
	s_waitcnt vmcnt(0)
	v_cmp_eq_u32_e32 vcc, v2, v3
	s_and_saveexec_b64 s[38:39], vcc
	s_cbranch_execz .LBB0_386
	s_mov_b32 s2, 1
	s_mov_b64 s[40:41], 0
	s_branch .LBB0_377

.LBB0_379:
	v_readlane_b32 s8, v251, 30
	v_readlane_b32 s9, v251, 31
	s_add_i32 s2, s2, 1
	s_mov_b64 s[48:49], -1
	s_nop 2
	global_load_dword v2, v99, s[8:9] sc1
	s_waitcnt vmcnt(0)
	v_cmp_ne_u32_e32 vcc, v2, v3
	s_orn2_b64 s[44:45], vcc, exec
	s_branch .LBB0_376

.LBB0_587:
	s_or_b64 exec, exec, s[22:23]
	v_cvt_f32_u32_e32 v6, v4
	s_waitcnt vmcnt(0)
	v_readfirstlane_b32 s4, v5
	v_sub_u32_e32 v5, 0, v4
	v_rcp_iflag_f32_e32 v6, v6
	v_add_u32_e32 v7, s4, v3
	v_mul_f32_e32 v6, 0x4f7ffffe, v6
	v_cvt_u32_f32_e32 v6, v6
	v_mul_lo_u32 v3, v5, v6
	v_mul_hi_u32 v3, v6, v3
	v_add_u32_e32 v3, v6, v3
	v_mul_hi_u32 v3, v7, v3
	v_mul_lo_u32 v5, v3, v4
	v_sub_u32_e32 v5, v7, v5
	v_add_u32_e32 v6, 1, v3
	v_cmp_ge_u32_e32 vcc, v5, v4
	s_nop 1
	v_cndmask_b32_e32 v3, v3, v6, vcc
	v_sub_u32_e32 v6, v5, v4
	v_cndmask_b32_e32 v5, v5, v6, vcc
	v_add_u32_e32 v6, 1, v3
	v_cmp_ge_u32_e32 vcc, v5, v4
	v_add_u32_e32 v5, 1, v7
	s_nop 0
	v_cndmask_b32_e32 v3, v3, v6, vcc
	v_mul_lo_u32 v6, v4, v3
	v_add_u32_e32 v4, v6, v4
	v_cmp_ne_u32_e32 vcc, v5, v4
	s_and_saveexec_b64 s[8:9], vcc
	s_xor_b64 s[22:23], exec, s[8:9]
	s_cbranch_execz .LBB0_601
	v_readlane_b32 s8, v251, 30
	v_readlane_b32 s9, v251, 31
	s_waitcnt lgkmcnt(0)
	s_nop 3
	global_load_dword v2, v99, s[8:9] sc1
	s_waitcnt vmcnt(0)
	v_cmp_eq_u32_e32 vcc, v2, v3
	s_and_saveexec_b64 s[36:37], vcc
	s_cbranch_execz .LBB0_600
	s_mov_b32 s4, 1
	s_mov_b64 s[38:39], 0
	s_branch .LBB0_591

.LBB0_593:
	v_readlane_b32 s8, v251, 30
	v_readlane_b32 s9, v251, 31
	s_add_i32 s4, s4, 1
	s_mov_b64 s[44:45], -1
	s_nop 2
	global_load_dword v2, v99, s[8:9] sc1
	s_waitcnt vmcnt(0)
	v_cmp_ne_u32_e32 vcc, v2, v3
	s_orn2_b64 s[42:43], vcc, exec
	s_branch .LBB0_590

.LBB0_720:
.LBB0_721:
	s_waitcnt vmcnt(0)
	v_lshlrev_b32_e32 v64, 16, v72
	v_lshlrev_b32_e32 v71, 16, v65
	v_lshlrev_b32_e32 v5, 16, v5
	v_mov_b32_e32 v120, v64
	v_mov_b32_e32 v121, v64
	s_nop 1
	v_permlane16_swap_b32_e32 v120, v121
	v_cndmask_b32_e64 v65, v120, v121, s[40:41]
	s_andn2_b64 vcc, exec, s[50:51]
	s_cbranch_vccnz .LBB0_723
	s_and_b32 s9, s7, 63
	s_bfe_u32 s10, s7, 0x50006
	v_mov_b32_e32 v72, s9
	v_mov_b32_e32 v73, s10
	v_cndmask_b32_e64 v72, v72, v73, s[38:39]
	v_lshlrev_b32_e32 v73, 2, v70
	v_lshl_or_b32 v72, v72, 6, v73
	v_or_b32_e32 v72, 0x26000, v72
	ds_read_b32 v73, v72 offset:4096
	s_waitcnt lgkmcnt(0)
	v_mul_f32_e32 v65, v73, v65
	ds_read_b32 v72, v72
	v_cndmask_b32_e64 v65, v65, -v65, s[40:41]
	s_waitcnt lgkmcnt(0)
	v_fmac_f32_e32 v65, v72, v64
	v_mov_b32_e32 v64, v65

.LBB0_725:
	s_andn2_b64 vcc, exec, s[48:49]
	s_cbranch_vccnz .LBB0_730
	v_mov_b32_e32 v120, v71
	v_mov_b32_e32 v121, v71
	s_nop 1
	v_permlane16_swap_b32_e32 v120, v121
	v_cndmask_b32_e64 v56, v120, v121, s[40:41]
	s_cmpk_gt_i32 s44, 0x3fff
	v_mov_b32_e32 v57, v71
	s_cbranch_scc1 .LBB0_728
	s_and_b32 s0, s44, 63
	s_bfe_u32 s1, s44, 0x50006
	v_mov_b32_e32 v57, s0
	v_mov_b32_e32 v58, s1
	v_cndmask_b32_e64 v57, v57, v58, s[38:39]
	v_lshlrev_b32_e32 v58, 2, v70
	v_lshl_or_b32 v57, v57, 6, v58
	v_or_b32_e32 v57, 0x26000, v57
	ds_read_b32 v58, v57 offset:4096
	s_waitcnt lgkmcnt(0)
	v_mul_f32_e32 v56, v58, v56
	ds_read_b32 v59, v57
	v_cndmask_b32_e64 v57, v56, -v56, s[40:41]
	s_waitcnt lgkmcnt(0)
	v_fmac_f32_e32 v57, v71, v59

.LBB0_730:
	s_andn2_b64 vcc, exec, s[42:43]
	s_cbranch_vccnz .LBB0_698
	v_mov_b32_e32 v120, v5
	v_mov_b32_e32 v121, v5
	s_nop 1
	v_permlane16_swap_b32_e32 v120, v121
	v_cndmask_b32_e64 v56, v120, v121, s[40:41]
	s_cmpk_gt_i32 s36, 0x3fff
	v_mov_b32_e32 v57, v5
	s_cbranch_scc1 .LBB0_733
	s_and_b32 s0, s36, 63
	s_bfe_u32 s1, s36, 0x50006
	v_mov_b32_e32 v57, s0
	v_mov_b32_e32 v58, s1
	v_cndmask_b32_e64 v57, v57, v58, s[38:39]
	v_lshlrev_b32_e32 v58, 2, v70
	v_lshl_or_b32 v57, v57, 6, v58
	v_or_b32_e32 v57, 0x26000, v57
	ds_read_b32 v58, v57 offset:4096
	s_waitcnt lgkmcnt(0)
	v_mul_f32_e32 v56, v58, v56
	ds_read_b32 v59, v57
	v_cndmask_b32_e64 v57, v56, -v56, s[40:41]
	s_waitcnt lgkmcnt(0)
	v_fmac_f32_e32 v57, v5, v59

.LBB0_1213:
	s_or_b64 exec, exec, s[22:23]
	v_cvt_f32_u32_e32 v6, v4
	s_waitcnt vmcnt(0)
	v_readfirstlane_b32 s2, v5
	v_sub_u32_e32 v5, 0, v4
	v_rcp_iflag_f32_e32 v6, v6
	v_add_u32_e32 v7, s2, v3
	v_mul_f32_e32 v6, 0x4f7ffffe, v6
	v_cvt_u32_f32_e32 v6, v6
	v_mul_lo_u32 v3, v5, v6
	v_mul_hi_u32 v3, v6, v3
	v_add_u32_e32 v3, v6, v3
	v_mul_hi_u32 v3, v7, v3
	v_mul_lo_u32 v5, v3, v4
	v_sub_u32_e32 v5, v7, v5
	v_add_u32_e32 v6, 1, v3
	v_cmp_ge_u32_e32 vcc, v5, v4
	s_nop 1
	v_cndmask_b32_e32 v3, v3, v6, vcc
	v_sub_u32_e32 v6, v5, v4
	v_cndmask_b32_e32 v5, v5, v6, vcc
	v_add_u32_e32 v6, 1, v3
	v_cmp_ge_u32_e32 vcc, v5, v4
	v_add_u32_e32 v5, 1, v7
	s_nop 0
	v_cndmask_b32_e32 v3, v3, v6, vcc
	v_mul_lo_u32 v6, v4, v3
	v_add_u32_e32 v4, v6, v4
	v_cmp_ne_u32_e32 vcc, v5, v4
	s_and_saveexec_b64 s[8:9], vcc
	s_xor_b64 s[22:23], exec, s[8:9]
	s_cbranch_execz .LBB0_1227
	v_readlane_b32 s8, v251, 30
	v_readlane_b32 s9, v251, 31
	s_waitcnt lgkmcnt(0)
	s_nop 3
	global_load_dword v2, v99, s[8:9] sc1
	s_waitcnt vmcnt(0)
	v_cmp_eq_u32_e32 vcc, v2, v3
	s_and_saveexec_b64 s[36:37], vcc
	s_cbranch_execz .LBB0_1226
	s_mov_b32 s2, 1
	s_mov_b64 s[38:39], 0
	s_branch .LBB0_1217

.LBB0_1271:
	s_or_b64 exec, exec, s[36:37]
	v_cvt_f32_u32_e32 v6, v4
	s_waitcnt vmcnt(0)
	v_readfirstlane_b32 s4, v5
	v_sub_u32_e32 v5, 0, v4
	v_rcp_iflag_f32_e32 v6, v6
	v_add_u32_e32 v7, s4, v3
	v_mul_f32_e32 v6, 0x4f7ffffe, v6
	v_cvt_u32_f32_e32 v6, v6
	v_mul_lo_u32 v3, v5, v6
	v_mul_hi_u32 v3, v6, v3
	v_add_u32_e32 v3, v6, v3
	v_mul_hi_u32 v3, v7, v3
	v_mul_lo_u32 v5, v3, v4
	v_sub_u32_e32 v5, v7, v5
	v_add_u32_e32 v6, 1, v3
	v_cmp_ge_u32_e32 vcc, v5, v4
	s_nop 1
	v_cndmask_b32_e32 v3, v3, v6, vcc
	v_sub_u32_e32 v6, v5, v4
	v_cndmask_b32_e32 v5, v5, v6, vcc
	v_add_u32_e32 v6, 1, v3
	v_cmp_ge_u32_e32 vcc, v5, v4
	v_add_u32_e32 v5, 1, v7
	s_nop 0
	v_cndmask_b32_e32 v3, v3, v6, vcc
	v_mul_lo_u32 v6, v4, v3
	v_add_u32_e32 v4, v6, v4
	v_cmp_ne_u32_e32 vcc, v5, v4
	s_and_saveexec_b64 s[8:9], vcc
	s_xor_b64 s[36:37], exec, s[8:9]
	s_cbranch_execz .LBB0_1285
	v_readlane_b32 s8, v251, 30
	v_readlane_b32 s9, v251, 31
	s_waitcnt lgkmcnt(0)
	s_nop 3
	global_load_dword v2, v99, s[8:9] sc1
	s_waitcnt vmcnt(0)
	v_cmp_eq_u32_e32 vcc, v2, v3
	s_and_saveexec_b64 s[38:39], vcc
	s_cbranch_execz .LBB0_1284
	s_mov_b32 s4, 1
	s_mov_b64 s[40:41], 0
	s_branch .LBB0_1275

.LBB0_1277:
	v_readlane_b32 s8, v251, 30
	v_readlane_b32 s9, v251, 31
	s_add_i32 s4, s4, 1
	s_mov_b64 s[48:49], -1
	s_nop 2
	global_load_dword v2, v99, s[8:9] sc1
	s_waitcnt vmcnt(0)
	v_cmp_ne_u32_e32 vcc, v2, v3
	s_orn2_b64 s[44:45], vcc, exec
	s_branch .LBB0_1274

.LBB0_1607:
	v_readlane_b32 s8, v251, 30
	v_readlane_b32 s9, v251, 31
	s_add_i32 s2, s2, 1
	s_mov_b64 s[46:47], -1
	s_nop 2
	global_load_dword v2, v99, s[8:9] sc1
	s_waitcnt vmcnt(0)
	v_cmp_ne_u32_e32 vcc, v2, v3
	s_orn2_b64 s[44:45], vcc, exec
	s_branch .LBB0_1604

.LBB0_1665:
	v_readlane_b32 s8, v251, 30
	v_readlane_b32 s9, v251, 31
	s_add_i32 s2, s2, 1
	s_mov_b64 s[44:45], -1
	s_nop 2
	global_load_dword v2, v99, s[8:9] sc1
	s_waitcnt vmcnt(0)
	v_cmp_ne_u32_e32 vcc, v2, v3
	s_orn2_b64 s[42:43], vcc, exec
	s_branch .LBB0_1662
